# three exposed load round trips removed: sample-attention unit start (wait before the first barrier), ssd_chunk_unit first loads issued together, ffn_act deferred-row loop mid-wait
# baseline (speedup 1.0000x reference)
.LBB0_413:
	s_ashr_i32 s44, s77, 5
	s_bfe_u32 s70, s77, 0x40001
	s_ashr_i32 s45, s44, 31
	s_lshl_b64 s[64:65], s[44:45], 11
	s_lshl_b32 s2, s70, 7
	s_or_b32 s24, s64, s2
	v_readlane_b32 s2, v253, 18
	v_readlane_b32 s3, v253, 19
	s_and_b32 s71, s77, 1
	s_mov_b32 s25, s65
	s_andn2_b64 vcc, exec, s[2:3]
	s_waitcnt vmcnt(0)
	s_barrier
	s_cbranch_vccnz .LBB0_425
	s_load_dwordx4 s[80:83], s[18:19], 0x68
	s_lshl_b32 s2, s71, 2
	s_or_b32 s33, s2, s88
	s_or_b32 s28, s33, s30
	s_lshl_b64 s[2:3], s[28:29], 2
	s_waitcnt lgkmcnt(0)
	s_add_u32 s26, s82, s2
	s_addc_u32 s27, s83, s3
	s_add_u32 s2, s80, s2
	s_addc_u32 s3, s81, s3
	global_load_dword v6, v96, s[26:27]
	global_load_dword v3, v96, s[2:3]
	v_lshl_add_u64 v[0:1], s[24:25], 0, v[106:107]
	v_mov_b64_e32 v[4:5], s[4:5]
	v_mad_u64_u32 v[4:5], s[2:3], v0, s42, v[4:5]
	v_mov_b32_e32 v22, v5
	s_lshl_b32 s28, s33, 2
	v_mad_u64_u32 v[8:9], s[2:3], v1, s42, v[22:23]
	v_mov_b32_e32 v5, v8
	v_lshl_add_u64 v[8:9], v[4:5], 0, s[28:29]
	v_add_co_u32_e32 v8, vcc, 0x1000, v8
	s_nop 1
	v_addc_co_u32_e32 v9, vcc, 0, v9, vcc
	global_load_dword v2, v[8:9], off offset:2048
	v_lshl_add_u64 v[26:27], v[4:5], 0, s[28:29]
	v_add_co_u32_e32 v26, vcc, 0x4000, v26
	s_nop 1
	v_addc_co_u32_e32 v27, vcc, 0, v27, vcc
	global_load_dword v24, v[26:27], off
	s_waitcnt vmcnt(0)
	v_add_f32_e32 v7, v3, v2
	v_cmp_nlt_f32_e32 vcc, 0, v7
	s_and_saveexec_b64 s[2:3], vcc
	s_xor_b64 s[26:27], exec, s[2:3]
	s_cbranch_execz .LBB0_416
	v_mul_f32_e32 v2, 0x3fb8aa3b, v7
	v_rndne_f32_e32 v8, v2
	s_mov_b32 s2, 0x3fb8aa3b
	v_sub_f32_e32 v9, v2, v8
	v_fma_f32 v2, v7, s2, -v2
	v_fmac_f32_e32 v2, 0x32a5705f, v7
	v_add_f32_e32 v2, v9, v2
	v_cvt_i32_f32_e32 v8, v8
	v_exp_f32_e32 v2, v2
	s_mov_b32 s2, 0xc2ce8ed0
	v_cmp_ngt_f32_e32 vcc, s2, v7
	s_mov_b32 s2, 0x42b17218
	v_ldexp_f32 v2, v2, v8
	v_cndmask_b32_e32 v2, 0, v2, vcc
	v_cmp_nlt_f32_e32 vcc, s2, v7
	s_mov_b32 s2, 0x3f2aaaab
	s_nop 0
	v_cndmask_b32_e32 v2, v179, v2, vcc
	v_add_f32_e32 v7, 1.0, v2
	v_add_f32_e32 v8, -1.0, v7
	v_sub_f32_e32 v9, v8, v7
	v_add_f32_e32 v9, 1.0, v9
	v_sub_f32_e32 v8, v2, v8
	v_add_f32_e32 v10, v8, v9
	v_frexp_mant_f32_e32 v11, v7
	v_cvt_f64_f32_e32 v[8:9], v7
	v_frexp_exp_i32_f64_e32 v8, v[8:9]
	v_cmp_gt_f32_e32 vcc, s2, v11
	s_mov_b32 s2, 0x3f317218
	s_nop 0
	v_subbrev_co_u32_e32 v16, vcc, 0, v8, vcc
	v_sub_u32_e32 v8, 0, v16
	v_ldexp_f32 v7, v7, v8
	v_ldexp_f32 v8, v10, v8
	v_add_f32_e32 v10, -1.0, v7
	v_add_f32_e32 v9, 1.0, v10
	v_sub_f32_e32 v9, v7, v9
	v_add_f32_e32 v11, v8, v9
	v_add_f32_e32 v9, 1.0, v7
	v_add_f32_e32 v12, -1.0, v9
	v_sub_f32_e32 v7, v7, v12
	v_add_f32_e32 v7, v8, v7
	v_add_f32_e32 v17, v9, v7
	v_rcp_f32_e32 v18, v17
	v_sub_f32_e32 v8, v9, v17
	v_add_f32_e32 v9, v10, v11
	v_add_f32_e32 v7, v7, v8
	v_mul_f32_e32 v20, v9, v18
	v_sub_f32_e32 v8, v10, v9
	v_mul_f32_e32 v10, v17, v20
	v_fma_f32 v12, v20, v17, -v10
	v_fmac_f32_e32 v12, v20, v7
	v_add_f32_e32 v19, v11, v8
	v_add_f32_e32 v8, v10, v12
	v_sub_f32_e32 v11, v9, v8
	v_pk_add_f32 v[14:15], v[8:9], v[10:11] neg_lo:[0,1] neg_hi:[0,1]
	v_mov_b32_e32 v13, v8
	v_pk_add_f32 v[8:9], v[14:15], v[12:13] neg_lo:[0,1] neg_hi:[0,1]
	s_nop 0
	v_add_f32_e32 v9, v19, v9
	v_add_f32_e32 v8, v8, v9
	v_add_f32_e32 v9, v11, v8
	v_mul_f32_e32 v19, v18, v9
	v_mul_f32_e32 v10, v17, v19
	v_fma_f32 v12, v19, v17, -v10
	v_fmac_f32_e32 v12, v19, v7
	v_sub_f32_e32 v7, v11, v9
	v_add_f32_e32 v7, v8, v7
	v_add_f32_e32 v8, v10, v12
	v_sub_f32_e32 v11, v9, v8
	v_pk_add_f32 v[14:15], v[8:9], v[10:11] neg_lo:[0,1] neg_hi:[0,1]
	v_mov_b32_e32 v13, v8
	v_pk_add_f32 v[8:9], v[14:15], v[12:13] neg_lo:[0,1] neg_hi:[0,1]
	s_nop 0
	v_add_f32_e32 v7, v7, v9
	v_add_f32_e32 v7, v8, v7
	v_add_f32_e32 v9, v20, v19
	v_add_f32_e32 v7, v11, v7
	v_sub_f32_e32 v8, v9, v20
	v_mul_f32_e32 v7, v18, v7
	v_sub_f32_e32 v8, v19, v8
	v_add_f32_e32 v7, v8, v7
	v_add_f32_e32 v10, v9, v7
	v_mul_f32_e32 v12, v10, v10
	v_fmamk_f32 v8, v12, 0x3e9b6dac, v176
	v_fmaak_f32 v147, v12, v8, 0x3f2aaada
	v_cvt_f32_i32_e32 v8, v16
	v_sub_f32_e32 v9, v10, v9
	v_sub_f32_e32 v7, v7, v9
	v_mul_f32_e32 v9, v10, v12
	v_pk_mul_f32 v[12:13], v[8:9], v[146:147]
	v_ldexp_f32 v11, v10, 1
	v_fma_f32 v10, v8, s2, -v12
	v_fmac_f32_e32 v10, 0xb102e308, v8
	v_pk_add_f32 v[8:9], v[12:13], v[10:11]
	v_ldexp_f32 v7, v7, 1
	v_sub_f32_e32 v11, v9, v11
	v_sub_f32_e32 v11, v13, v11
	v_add_f32_e32 v15, v7, v11
	v_mov_b32_e32 v14, v12
	v_pk_add_f32 v[12:13], v[8:9], v[12:13] neg_lo:[0,1] neg_hi:[0,1]
	v_pk_add_f32 v[16:17], v[8:9], v[14:15]
	v_mov_b32_e32 v11, v8
	v_mov_b32_e32 v13, v17
	v_pk_add_f32 v[18:19], v[10:11], v[12:13] neg_lo:[0,1] neg_hi:[0,1]
	v_pk_add_f32 v[10:11], v[10:11], v[12:13]
	v_mov_b32_e32 v14, v15
	v_pk_add_f32 v[12:13], v[10:11], v[8:9] op_sel:[1,0] op_sel_hi:[0,1] neg_lo:[0,1] neg_hi:[0,1]
	v_pk_add_f32 v[20:21], v[16:17], v[12:13] op_sel_hi:[1,0] neg_lo:[0,1] neg_hi:[0,1]
	v_mov_b32_e32 v16, v17
	v_mov_b32_e32 v17, v11
	v_pk_mov_b32 v[12:13], v[8:9], v[12:13] op_sel:[1,0]
	v_mov_b32_e32 v15, v8
	v_pk_add_f32 v[12:13], v[16:17], v[12:13] neg_lo:[0,1] neg_hi:[0,1]
	v_mov_b32_e32 v20, v18
	v_pk_add_f32 v[8:9], v[14:15], v[12:13] neg_lo:[0,1] neg_hi:[0,1]
	v_mov_b32_e32 v19, v11
	v_pk_add_f32 v[12:13], v[20:21], v[8:9]
	s_mov_b32 s2, 0x7f800000
	v_pk_add_f32 v[14:15], v[12:13], v[12:13] op_sel:[0,1] op_sel_hi:[1,0]
	v_cmp_neq_f32_e32 vcc, s2, v2
	v_pk_add_f32 v[10:11], v[10:11], v[14:15] op_sel:[1,0] op_sel_hi:[0,1]
	v_mov_b32_e32 v13, v10
	v_pk_add_f32 v[16:17], v[12:13], v[18:19] neg_lo:[0,1] neg_hi:[0,1]
	v_mov_b32_e32 v9, v14
	v_sub_f32_e32 v7, v12, v16
	v_pk_add_f32 v[8:9], v[8:9], v[16:17] neg_lo:[0,1] neg_hi:[0,1]
	v_sub_f32_e32 v7, v18, v7
	v_add_f32_e32 v7, v8, v7
	v_add_f32_e32 v7, v7, v9
	v_add_f32_e32 v7, v10, v7
	s_mov_b32 s2, 0x33800000
	v_cndmask_b32_e32 v7, v179, v7, vcc
	v_cmp_lt_f32_e64 vcc, |v2|, s2
	s_nop 1
	v_cndmask_b32_e32 v2, v7, v2, vcc

.LBB0_418:
	s_or_b64 exec, exec, s[26:27]
	v_mov_b32_e32 v4, v24
	v_add_f32_e32 v4, v3, v4
	v_cmp_nlt_f32_e32 vcc, 0, v4
	s_and_saveexec_b64 s[2:3], vcc
	v_readlane_b32 s82, v255, 12
	s_xor_b64 s[26:27], exec, s[2:3]
	v_readlane_b32 s80, v255, 11
	v_readlane_b32 s83, v255, 13
	v_readlane_b32 s81, v255, 14
	s_cbranch_execz .LBB0_420
	v_mul_f32_e32 v3, 0x3fb8aa3b, v4
	v_rndne_f32_e32 v5, v3
	s_mov_b32 s2, 0x3fb8aa3b
	v_sub_f32_e32 v7, v3, v5
	v_fma_f32 v3, v4, s2, -v3
	v_fmac_f32_e32 v3, 0x32a5705f, v4
	v_add_f32_e32 v3, v7, v3
	v_cvt_i32_f32_e32 v5, v5
	v_exp_f32_e32 v3, v3
	s_mov_b32 s2, 0xc2ce8ed0
	v_cmp_ngt_f32_e32 vcc, s2, v4
	s_mov_b32 s2, 0x42b17218
	v_ldexp_f32 v3, v3, v5
	v_cndmask_b32_e32 v3, 0, v3, vcc
	v_cmp_nlt_f32_e32 vcc, s2, v4
	s_mov_b32 s2, 0x3f2aaaab
	s_nop 0
	v_cndmask_b32_e32 v3, v179, v3, vcc
	v_add_f32_e32 v7, 1.0, v3
	v_add_f32_e32 v4, -1.0, v7
	v_sub_f32_e32 v5, v4, v7
	v_add_f32_e32 v5, 1.0, v5
	v_sub_f32_e32 v4, v3, v4
	v_add_f32_e32 v8, v4, v5
	v_frexp_mant_f32_e32 v9, v7
	v_cvt_f64_f32_e32 v[4:5], v7
	v_frexp_exp_i32_f64_e32 v4, v[4:5]
	v_cmp_gt_f32_e32 vcc, s2, v9
	s_mov_b32 s2, 0x3f317218
	s_nop 0
	v_subbrev_co_u32_e32 v14, vcc, 0, v4, vcc
	v_sub_u32_e32 v4, 0, v14
	v_ldexp_f32 v5, v7, v4
	v_add_f32_e32 v7, -1.0, v5
	v_add_f32_e32 v9, 1.0, v5
	v_ldexp_f32 v4, v8, v4
	v_add_f32_e32 v8, 1.0, v7
	v_add_f32_e32 v10, -1.0, v9
	v_sub_f32_e32 v8, v5, v8
	v_sub_f32_e32 v5, v5, v10
	v_add_f32_e32 v8, v4, v8
	v_add_f32_e32 v4, v4, v5
	v_add_f32_e32 v15, v9, v4
	v_rcp_f32_e32 v17, v15
	v_sub_f32_e32 v5, v9, v15
	v_add_f32_e32 v16, v4, v5
	v_add_f32_e32 v5, v7, v8
	v_sub_f32_e32 v4, v7, v5
	v_mul_f32_e32 v18, v5, v17
	v_add_f32_e32 v7, v8, v4
	v_mul_f32_e32 v8, v15, v18
	v_fma_f32 v10, v18, v15, -v8
	v_fmac_f32_e32 v10, v18, v16
	v_add_f32_e32 v4, v8, v10
	v_sub_f32_e32 v9, v5, v4
	v_pk_add_f32 v[12:13], v[4:5], v[8:9] neg_lo:[0,1] neg_hi:[0,1]
	v_mov_b32_e32 v11, v4
	v_pk_add_f32 v[4:5], v[12:13], v[10:11] neg_lo:[0,1] neg_hi:[0,1]
	s_nop 0
	v_add_f32_e32 v5, v7, v5
	v_add_f32_e32 v4, v4, v5
	v_add_f32_e32 v5, v9, v4
	v_mul_f32_e32 v7, v17, v5
	v_mul_f32_e32 v8, v15, v7
	v_fma_f32 v10, v7, v15, -v8
	v_fmac_f32_e32 v10, v7, v16
	v_sub_f32_e32 v9, v9, v5
	v_add_f32_e32 v15, v4, v9
	v_add_f32_e32 v4, v8, v10
	v_sub_f32_e32 v9, v5, v4
	v_pk_add_f32 v[12:13], v[4:5], v[8:9] neg_lo:[0,1] neg_hi:[0,1]
	v_mov_b32_e32 v11, v4
	v_pk_add_f32 v[4:5], v[12:13], v[10:11] neg_lo:[0,1] neg_hi:[0,1]
	s_nop 0
	v_add_f32_e32 v5, v15, v5
	v_add_f32_e32 v4, v4, v5
	v_add_f32_e32 v5, v18, v7
	v_add_f32_e32 v4, v9, v4
	v_sub_f32_e32 v8, v5, v18
	v_mul_f32_e32 v4, v17, v4
	v_sub_f32_e32 v7, v7, v8
	v_add_f32_e32 v7, v7, v4
	v_add_f32_e32 v8, v5, v7
	v_mul_f32_e32 v10, v8, v8
	v_fmamk_f32 v4, v10, 0x3e9b6dac, v176
	v_fmaak_f32 v147, v10, v4, 0x3f2aaada
	v_cvt_f32_i32_e32 v4, v14
	v_sub_f32_e32 v5, v8, v5
	v_sub_f32_e32 v5, v7, v5
	v_ldexp_f32 v7, v5, 1
	v_mul_f32_e32 v5, v8, v10
	v_pk_mul_f32 v[10:11], v[4:5], v[146:147]
	v_ldexp_f32 v9, v8, 1
	v_fma_f32 v8, v4, s2, -v10
	v_fmac_f32_e32 v8, 0xb102e308, v4
	v_pk_add_f32 v[4:5], v[10:11], v[8:9]
	v_mov_b32_e32 v12, v10
	v_sub_f32_e32 v9, v5, v9
	v_sub_f32_e32 v9, v11, v9
	v_add_f32_e32 v13, v7, v9
	v_pk_add_f32 v[10:11], v[4:5], v[10:11] neg_lo:[0,1] neg_hi:[0,1]
	v_pk_add_f32 v[14:15], v[4:5], v[12:13]
	v_mov_b32_e32 v9, v4
	v_mov_b32_e32 v11, v15
	v_pk_add_f32 v[16:17], v[8:9], v[10:11] neg_lo:[0,1] neg_hi:[0,1]
	v_pk_add_f32 v[8:9], v[8:9], v[10:11]
	v_mov_b32_e32 v12, v13
	v_pk_add_f32 v[10:11], v[8:9], v[4:5] op_sel:[1,0] op_sel_hi:[0,1] neg_lo:[0,1] neg_hi:[0,1]
	v_pk_add_f32 v[18:19], v[14:15], v[10:11] op_sel_hi:[1,0] neg_lo:[0,1] neg_hi:[0,1]
	v_mov_b32_e32 v14, v15
	v_mov_b32_e32 v15, v9
	v_pk_mov_b32 v[10:11], v[4:5], v[10:11] op_sel:[1,0]
	v_mov_b32_e32 v13, v4
	v_pk_add_f32 v[10:11], v[14:15], v[10:11] neg_lo:[0,1] neg_hi:[0,1]
	v_mov_b32_e32 v18, v16
	v_pk_add_f32 v[4:5], v[12:13], v[10:11] neg_lo:[0,1] neg_hi:[0,1]
	v_mov_b32_e32 v17, v9
	v_pk_add_f32 v[10:11], v[18:19], v[4:5]
	s_mov_b32 s2, 0x7f800000
	v_pk_add_f32 v[12:13], v[10:11], v[10:11] op_sel:[0,1] op_sel_hi:[1,0]
	v_cmp_neq_f32_e32 vcc, s2, v3
	v_pk_add_f32 v[8:9], v[8:9], v[12:13] op_sel:[1,0] op_sel_hi:[0,1]
	v_mov_b32_e32 v11, v8
	v_pk_add_f32 v[14:15], v[10:11], v[16:17] neg_lo:[0,1] neg_hi:[0,1]
	v_mov_b32_e32 v5, v12
	v_sub_f32_e32 v7, v10, v14
	v_pk_add_f32 v[4:5], v[4:5], v[14:15] neg_lo:[0,1] neg_hi:[0,1]
	v_sub_f32_e32 v7, v16, v7
	v_add_f32_e32 v4, v4, v7
	v_add_f32_e32 v4, v4, v5
	v_add_f32_e32 v4, v8, v4
	s_mov_b32 s2, 0x33800000
	v_cndmask_b32_e32 v4, v179, v4, vcc
	v_cmp_lt_f32_e64 vcc, |v3|, s2
	s_nop 1
	v_cndmask_b32_e32 v3, v4, v3, vcc

.LBB0_716:
	s_and_b32 s68, s67, 7
	s_lshl_b32 s68, s68, 2
	s_lshr_b32 s69, s67, 6
	s_add_i32 s68, s68, s69
	s_lshl_b32 s68, s68, 3
	s_bfe_u32 s69, s67, 0x30003
	s_or_b32 s2, s68, s69
	s_and_b32 s68, s2, 7
	s_and_b32 s69, s2, -8
	s_or_b32 s2, s69, s68
	s_add_i32 s58, s2, 0x4000
	s_ashr_i32 s59, s58, 31
	v_mov_b32_e32 v133, v134
	s_lshl_b64 s[2:3], s[58:59], 9
	s_add_u32 s2, s28, s2
	v_ashrrev_i32_e32 v97, 5, v133
	s_waitcnt vmcnt(0)
	v_and_b32_e32 v83, 3, v133
	s_addc_u32 s3, s30, s3
	v_lshlrev_b32_e32 v0, 7, v83
	v_mov_b32_e32 v1, v96
	v_lshlrev_b32_e32 v2, 3, v97
	v_lshl_add_u64 v[0:1], s[2:3], 0, v[0:1]
	v_ashrrev_i32_e32 v3, 31, v2
	v_lshl_add_u64 v[0:1], v[2:3], 1, v[0:1]
	s_mul_i32 s2, s58, 0x2800
	global_load_dwordx4 v[48:51], v[0:1], off
	global_load_dwordx4 v[52:55], v[0:1], off offset:32
	global_load_dwordx4 v[56:59], v[0:1], off offset:64
	global_load_dwordx4 v[60:63], v[0:1], off offset:96
	s_mul_hi_i32 s3, s58, 0x2800
	s_add_u32 s2, s14, s2
	v_mul_u32_u24_e32 v0, 3, v83
	s_addc_u32 s3, s15, s3
	v_lshlrev_b32_e32 v0, 2, v0
	v_mov_b32_e32 v1, v96
	v_lshl_add_u64 v[0:1], s[2:3], 0, v[0:1]
	s_mov_b32 s2, 0xdea2000
	v_add_co_u32_e32 v0, vcc, s2, v0
	v_add_u32_e32 v104, s90, v133
	s_nop 0
	v_addc_co_u32_e32 v1, vcc, 0, v1, vcc
	global_load_dwordx3 v[80:82], v[0:1], off offset:2080
	v_cmp_gt_i32_e32 vcc, 64, v104
	v_lshl_add_u32 v105, v104, 2, 0
	s_barrier
	s_and_saveexec_b64 s[4:5], vcc
	v_add_u32_e32 v0, 0x13000, v105
	ds_write_b32 v0, v96
	s_or_b64 exec, exec, s[4:5]
	v_mov_b32_e32 v2, v133
	v_readlane_b32 s2, v254, 40
	v_ashrrev_i32_e32 v0, 1, v2
	s_ashr_i32 s62, s58, 3
	s_addk_i32 s62, 0xf800
	v_add_u32_e32 v0, s2, v0
	s_movk_i32 s2, 0x1ff
	v_cmp_gt_i32_e32 vcc, s2, v0
	s_ashr_i32 s63, s62, 31
	s_add_u32 s6, s16, s62
	v_cndmask_b32_e32 v0, 0, v0, vcc
	s_addc_u32 s7, s17, s63
	v_ashrrev_i32_e32 v1, 31, v0
	v_mov_b32_e32 v3, 0x1ff
	s_mulk_i32 s7, 0x1ff
	v_mad_u64_u32 v[0:1], s[2:3], s6, v3, v[0:1]
	v_add_u32_e32 v1, s7, v1
	v_lshlrev_b64 v[0:1], 8, v[0:1]
	v_lshlrev_b32_e32 v2, 7, v2
	v_lshl_add_u64 v[0:1], s[22:23], 0, v[0:1]
	v_and_b32_e32 v2, 0x80, v2
	v_mov_b32_e32 v3, v96
	v_lshl_add_u64 v[16:17], v[0:1], 0, v[2:3]
	v_mov_b32_e32 v0, 0
	v_mov_b32_e32 v4, 0
	v_mov_b32_e32 v5, 0
	v_mov_b32_e32 v6, 0
	v_mov_b32_e32 v7, 0
	v_mov_b32_e32 v8, 0
	v_mov_b32_e32 v9, 0
	v_mov_b32_e32 v10, 0
	v_mov_b32_e32 v11, 0
	s_and_saveexec_b64 s[4:5], vcc
	s_cbranch_execz .LBB0_720
	global_load_dwordx4 v[4:7], v[16:17], off
	global_load_dwordx4 v[8:11], v[16:17], off offset:16

.LBB0_734:
	s_or_b64 exec, exec, s[4:5]
	v_mov_b32_e32 v84, v133
	s_waitcnt vmcnt(1)
	v_cvt_pk_bf16_f32 v4, v4, v5
	v_ashrrev_i32_e32 v85, 1, v84
	v_lshl_add_u32 v86, v85, 7, s41
	v_lshlrev_b32_e32 v84, 2, v84
	v_and_b32_e32 v85, 7, v85
	v_cvt_pk_bf16_f32 v5, v6, v7
	s_waitcnt vmcnt(0)
	v_cmp_nlt_f32_e64 s[54:55], s34, v80
	v_cmp_ngt_f32_e64 s[56:57], s35, v80
	v_cmp_nlt_f32_e64 s[50:51], s34, v81
	v_cmp_ngt_f32_e64 s[46:47], s35, v81
	v_cmp_nlt_f32_e64 s[52:53], s34, v82
	v_cmp_ngt_f32_e64 s[48:49], s35, v82
	v_cvt_pk_bf16_f32 v6, v8, v9
	v_bitop3_b32 v8, v84, v85, 4 bitop3:0x6c
	v_and_b32_e32 v87, 4, v84
	v_cvt_pk_bf16_f32 v7, v10, v11
	v_lshl_add_u32 v8, v8, 4, v86
	ds_write_b128 v8, v[4:7]
	v_bitop3_b32 v4, v87, v85, 1 bitop3:0x36
	v_cvt_pk_bf16_f32 v0, v0, v1
	v_cvt_pk_bf16_f32 v1, v2, v3
	v_cvt_pk_bf16_f32 v2, v12, v13
	v_cvt_pk_bf16_f32 v3, v14, v15
	v_lshl_add_u32 v4, v4, 4, v86
	ds_write_b128 v4, v[0:3]
	v_bitop3_b32 v4, v87, v85, 2 bitop3:0x36
	v_cvt_pk_bf16_f32 v0, v32, v33
	v_cvt_pk_bf16_f32 v1, v34, v35
	v_cvt_pk_bf16_f32 v2, v36, v37
	v_cvt_pk_bf16_f32 v3, v38, v39
	v_lshl_add_u32 v4, v4, 4, v86
	ds_write_b128 v4, v[0:3]
	v_bitop3_b32 v4, v87, v85, 3 bitop3:0x36
	v_cvt_pk_bf16_f32 v0, v20, v21
	v_cvt_pk_bf16_f32 v1, v22, v23
	v_cvt_pk_bf16_f32 v2, v44, v45
	v_cvt_pk_bf16_f32 v3, v46, v47
	v_lshl_add_u32 v4, v4, 4, v86
	ds_write_b128 v4, v[0:3]
	v_mov_b32_e32 v32, v133
	s_waitcnt lgkmcnt(0)
	v_lshlrev_b32_e32 v132, 2, v97
	v_lshlrev_b32_e32 v0, 7, v32
	v_ashrrev_i32_e32 v33, 5, v32
	v_and_b32_e32 v0, 0xf80, v0
	v_add_u32_e32 v34, s41, v0
	v_bitop3_b32 v0, v33, v32, 7 bitop3:0x78
	v_lshl_add_u32 v0, v0, 4, v34
	ds_read_b128 v[0:3], v0
	v_add_u32_e32 v4, 2, v33
	v_bitop3_b32 v4, v4, v32, 7 bitop3:0x78
	v_lshl_add_u32 v4, v4, 4, v34
	ds_read_b128 v[20:23], v4
	s_waitcnt lgkmcnt(1)
	v_mfma_f32_32x32x16_bf16 v[0:15], v[0:3], v[48:51], 0
	v_readlane_b32 s3, v254, 40
	s_movk_i32 s7, 0x1fe
	s_movk_i32 s8, 0x1fd
	s_movk_i32 s6, 0xfe00
	v_readlane_b32 s2, v253, 44
	s_waitcnt lgkmcnt(0)
	v_mfma_f32_32x32x16_bf16 v[0:15], v[20:23], v[52:55], v[0:15]
	v_add_u32_e32 v20, 4, v33
	v_bitop3_b32 v20, v20, v32, 7 bitop3:0x78
	v_lshl_add_u32 v20, v20, 4, v34
	ds_read_b128 v[20:23], v20
	v_add_u32_e32 v33, 6, v33
	v_bitop3_b32 v32, v33, v32, 7 bitop3:0x78
	v_lshl_add_u32 v32, v32, 4, v34
	ds_read_b128 v[32:35], v32
	s_waitcnt lgkmcnt(1)
	v_mfma_f32_32x32x16_bf16 v[0:15], v[20:23], v[56:59], v[0:15]
	s_waitcnt lgkmcnt(0)
	s_waitcnt lgkmcnt(0)
	v_mfma_f32_32x32x16_bf16 v[0:15], v[32:35], v[60:63], v[0:15]
	v_add_u32_e32 v32, s3, v132
	v_cmp_lt_u32_e32 vcc, s7, v32
	v_cmp_lt_u32_e64 s[4:5], s8, v32
	s_and_b64 vcc, s[4:5], vcc
	s_nop 7
	v_cndmask_b32_e32 v95, v0, v181, vcc
	v_or_b32_e32 v0, 3, v32
	v_cndmask_b32_e64 v86, v2, v181, s[4:5]
	v_cndmask_b32_e64 v94, v1, v181, s[4:5]
	v_cmp_gt_i32_e32 vcc, 0, v32
	v_cmp_lt_i32_e64 s[4:5], s7, v0
	s_or_b64 vcc, vcc, s[4:5]
	v_add_u32_e32 v0, 0xfffffe09, v32
	v_cndmask_b32_e32 v93, v3, v181, vcc
	v_cmp_lt_u32_e32 vcc, s6, v0
	v_add_u32_e32 v0, 0xfffffe0a, v32
	v_cvt_pk_bf16_f32 v2, v28, v29
	v_cndmask_b32_e32 v87, v181, v4, vcc
	v_cmp_lt_u32_e32 vcc, s6, v0
	v_add_u32_e32 v0, 0xfffffe0b, v32
	v_cvt_pk_bf16_f32 v3, v30, v31
	v_cndmask_b32_e32 v92, v181, v5, vcc
	v_cmp_lt_u32_e32 vcc, s6, v0
	v_add_u32_e32 v0, 0xfffffe0c, v32
	s_nop 0
	v_cndmask_b32_e32 v90, v181, v6, vcc
	v_cmp_lt_u32_e32 vcc, s6, v0
	v_add_u32_e32 v0, 0xfffffe11, v32
	s_nop 0
	v_cndmask_b32_e32 v91, v181, v7, vcc
	v_cmp_lt_u32_e32 vcc, s6, v0
	v_add_u32_e32 v0, 0xfffffe12, v32
	s_nop 0
	v_cndmask_b32_e32 v88, v181, v8, vcc
	v_cmp_lt_u32_e32 vcc, s6, v0
	v_mov_b32_e32 v0, v133
	v_mov_b32_e32 v8, v133
	v_ashrrev_i32_e32 v1, 1, v0
	v_lshlrev_b32_e32 v5, 2, v0
	v_and_b32_e32 v7, 7, v1
	v_lshl_add_u32 v4, v1, 7, s41
	v_and_b32_e32 v6, 4, v5
	v_bitop3_b32 v5, v5, v7, 4 bitop3:0x6c
	v_cvt_pk_bf16_f32 v0, v24, v25
	v_cvt_pk_bf16_f32 v1, v26, v27
	v_lshl_add_u32 v5, v5, 4, v4
	ds_write_b128 v5, v[0:3]
	v_bitop3_b32 v5, v6, v7, 1 bitop3:0x36
	v_cvt_pk_bf16_f32 v0, v16, v17
	v_cvt_pk_bf16_f32 v1, v18, v19
	v_cvt_pk_bf16_f32 v2, v40, v41
	v_cvt_pk_bf16_f32 v3, v42, v43
	v_lshl_add_u32 v5, v5, 4, v4
	ds_write_b128 v5, v[0:3]
	v_bitop3_b32 v5, v6, v7, 2 bitop3:0x36
	v_cvt_pk_bf16_f32 v0, v68, v69
	v_cvt_pk_bf16_f32 v1, v70, v71
	v_cvt_pk_bf16_f32 v2, v72, v73
	v_cvt_pk_bf16_f32 v3, v74, v75
	v_lshl_add_u32 v5, v5, 4, v4
	ds_write_b128 v5, v[0:3]
	v_bitop3_b32 v5, v6, v7, 3 bitop3:0x36
	v_cvt_pk_bf16_f32 v0, v64, v65
	v_cvt_pk_bf16_f32 v1, v66, v67
	v_cvt_pk_bf16_f32 v2, v76, v77
	v_cvt_pk_bf16_f32 v3, v78, v79
	v_lshl_add_u32 v4, v5, 4, v4
	ds_write_b128 v4, v[0:3]
	s_waitcnt lgkmcnt(0)
	v_cndmask_b32_e32 v89, v181, v9, vcc
	v_lshlrev_b32_e32 v0, 7, v8
	v_ashrrev_i32_e32 v9, 5, v8
	v_and_b32_e32 v0, 0xf80, v0
	v_add_u32_e32 v33, s41, v0
	v_bitop3_b32 v0, v9, v8, 7 bitop3:0x78
	v_lshl_add_u32 v0, v0, 4, v33
	ds_read_b128 v[0:3], v0
	v_add_u32_e32 v4, 0xfffffe13, v32
	v_cmp_lt_u32_e32 vcc, s6, v4
	v_add_u32_e32 v4, 2, v9
	v_bitop3_b32 v4, v4, v8, 7 bitop3:0x78
	v_lshl_add_u32 v4, v4, 4, v33
	ds_read_b128 v[4:7], v4
	s_waitcnt lgkmcnt(1)
	v_mfma_f32_32x32x16_bf16 v[16:31], v[0:3], v[48:51], 0
	v_add_u32_e32 v0, 4, v9
	v_bitop3_b32 v0, v0, v8, 7 bitop3:0x78
	v_lshl_add_u32 v0, v0, 4, v33
	ds_read_b128 v[0:3], v0
	v_cndmask_b32_e32 v100, v181, v10, vcc
	v_add_u32_e32 v10, 0xfffffe14, v32
	v_cmp_lt_u32_e32 vcc, s6, v10
	s_waitcnt lgkmcnt(1)
	v_mfma_f32_32x32x16_bf16 v[16:31], v[4:7], v[52:55], v[16:31]
	v_add_u32_e32 v4, 6, v9
	v_bitop3_b32 v4, v4, v8, 7 bitop3:0x78
	v_lshl_add_u32 v4, v4, 4, v33
	ds_read_b128 v[4:7], v4
	v_add_u32_e32 v10, 0xfffffe19, v32
	v_cndmask_b32_e32 v101, v181, v11, vcc
	v_cmp_lt_u32_e32 vcc, s6, v10
	s_waitcnt lgkmcnt(1)
	v_mfma_f32_32x32x16_bf16 v[16:31], v[0:3], v[56:59], v[16:31]
	v_add_u32_e32 v10, 0xfffffe1a, v32
	v_cndmask_b32_e32 v122, v181, v12, vcc
	v_cmp_lt_u32_e32 vcc, s6, v10
	v_add_u32_e32 v0, 0xfffffe1b, v32
	v_mov_b32_e32 v8, 0
	v_cndmask_b32_e32 v125, v181, v13, vcc
	v_cmp_lt_u32_e32 vcc, s6, v0
	s_waitcnt lgkmcnt(0)
	v_mfma_f32_32x32x16_bf16 v[16:31], v[4:7], v[60:63], v[16:31]
	v_add_u32_e32 v0, 0xfffffe1c, v32
	v_cndmask_b32_e32 v123, v181, v14, vcc
	v_cmp_lt_u32_e32 vcc, s6, v0
	v_add_u32_e32 v0, s2, v132
	v_cmp_lt_u32_e64 s[4:5], s8, v0
	v_cndmask_b32_e32 v124, v181, v15, vcc
	v_cmp_lt_u32_e32 vcc, s7, v0
	s_and_b64 vcc, s[4:5], vcc
	v_or_b32_e32 v1, 3, v0
	s_nop 2
	v_cndmask_b32_e64 v111, v18, v181, s[4:5]
	v_cndmask_b32_e32 v121, v16, v181, vcc
	v_cndmask_b32_e64 v120, v17, v181, s[4:5]
	v_cmp_gt_i32_e32 vcc, 0, v0
	v_cmp_lt_i32_e64 s[4:5], s7, v1
	s_or_b64 vcc, vcc, s[4:5]
	v_add_u32_e32 v1, 0xfffffe09, v0
	v_cndmask_b32_e32 v119, v19, v181, vcc
	v_cmp_lt_u32_e32 vcc, s6, v1
	v_add_u32_e32 v1, 0xfffffe0a, v0
	v_max_f32_e32 v2, v120, v120
	v_cndmask_b32_e32 v116, v181, v20, vcc
	v_cmp_lt_u32_e32 vcc, s6, v1
	v_add_u32_e32 v1, 0xfffffe0b, v0
	v_max_f32_e32 v3, v121, v121
	v_cndmask_b32_e32 v118, v181, v21, vcc
	v_cmp_lt_u32_e32 vcc, s6, v1
	v_add_u32_e32 v1, 0xfffffe0c, v0
	v_max_f32_e32 v2, v3, v2
	v_cndmask_b32_e32 v115, v181, v22, vcc
	v_cmp_lt_u32_e32 vcc, s6, v1
	v_add_u32_e32 v1, 0xfffffe11, v0
	v_max3_f32 v2, v2, v111, v119
	v_cndmask_b32_e32 v117, v181, v23, vcc
	v_cmp_lt_u32_e32 vcc, s6, v1
	v_add_u32_e32 v1, 0xfffffe12, v0
	v_max3_f32 v2, v2, v116, v118
	v_cndmask_b32_e32 v112, v181, v24, vcc
	v_cmp_lt_u32_e32 vcc, s6, v1
	v_add_u32_e32 v1, 0xfffffe13, v0
	v_max3_f32 v2, v2, v115, v117
	v_cndmask_b32_e32 v114, v181, v25, vcc
	v_cmp_lt_u32_e32 vcc, s6, v1
	v_add_u32_e32 v1, 0xfffffe14, v0
	v_max3_f32 v2, v2, v112, v114
	v_cndmask_b32_e32 v108, v181, v26, vcc
	v_cmp_lt_u32_e32 vcc, s6, v1
	v_add_u32_e32 v1, 0xfffffe19, v0
	v_readlane_b32 s2, v253, 43
	v_cndmask_b32_e32 v113, v181, v27, vcc
	v_cmp_lt_u32_e32 vcc, s6, v1
	v_add_u32_e32 v1, 0xfffffe1a, v0
	v_max3_f32 v2, v2, v108, v113
	v_cndmask_b32_e32 v107, v181, v28, vcc
	v_cmp_lt_u32_e32 vcc, s6, v1
	v_add_u32_e32 v1, 0xfffffe1b, v0
	v_add_u32_e32 v0, 0xfffffe1c, v0
	v_cndmask_b32_e32 v109, v181, v29, vcc
	v_cmp_lt_u32_e32 vcc, s6, v1
	v_max_f32_e32 v1, v95, v95
	v_max3_f32 v2, v2, v107, v109
	v_cndmask_b32_e32 v106, v181, v30, vcc
	v_cmp_lt_u32_e32 vcc, s6, v0
	v_max_f32_e32 v0, v94, v94
	v_max_f32_e32 v0, v1, v0
	v_max3_f32 v0, v0, v86, v93
	v_max3_f32 v0, v0, v87, v92
	v_max3_f32 v0, v0, v90, v91
	v_cndmask_b32_e32 v110, v181, v31, vcc
	v_max3_f32 v0, v0, v88, v89
	v_max3_f32 v0, v0, v100, v101
	v_max3_f32 v2, v2, v106, v110
	v_max3_f32 v0, v0, v122, v125
	v_mov_b32_e32 v3, v2
	v_max3_f32 v0, v0, v123, v124
	s_nop 0
	v_permlane32_swap_b32_e32 v2, v3
	v_mov_b32_e32 v1, v0
	v_max_f32_e32 v3, v3, v3
	v_max_f32_e32 v2, v2, v2
	v_permlane32_swap_b32_e32 v0, v1
	v_max_f32_e32 v2, v2, v3
	v_max3_f32 v1, v0, v1, v2
	v_sub_f32_e32 v0, v95, v1
	v_exp_f32_e32 v2, v0
	v_sub_f32_e32 v0, v121, v1
	v_exp_f32_e32 v3, v0
	v_sub_f32_e32 v0, v94, v1
	v_exp_f32_e32 v4, v0
	v_sub_f32_e32 v0, v120, v1
	v_exp_f32_e32 v5, v0
	v_add_f32_e32 v2, v2, v3
	v_sub_f32_e32 v6, v93, v1
	v_sub_f32_e32 v7, v119, v1
	v_add_f32_e32 v3, v4, v5
	v_sub_f32_e32 v4, v86, v1
	v_sub_f32_e32 v5, v111, v1
	v_exp_f32_e32 v4, v4
	v_exp_f32_e32 v5, v5
	v_exp_f32_e32 v6, v6
	v_exp_f32_e32 v7, v7
	v_add_f32_e32 v2, 0, v2
	v_add_f32_e32 v2, v3, v2
	v_add_f32_e32 v3, v4, v5
	v_sub_f32_e32 v4, v87, v1
	v_sub_f32_e32 v5, v116, v1
	v_add_f32_e32 v2, v3, v2
	v_add_f32_e32 v3, v6, v7
	v_exp_f32_e32 v4, v4
	v_exp_f32_e32 v5, v5
	v_sub_f32_e32 v6, v92, v1
	v_sub_f32_e32 v7, v118, v1
	v_exp_f32_e32 v6, v6
	v_exp_f32_e32 v7, v7
	v_add_f32_e32 v2, v3, v2
	v_add_f32_e32 v3, v4, v5
	v_sub_f32_e32 v4, v90, v1
	v_sub_f32_e32 v5, v115, v1
	v_add_f32_e32 v2, v3, v2
	v_add_f32_e32 v3, v6, v7
	v_exp_f32_e32 v4, v4
	v_exp_f32_e32 v5, v5
	v_sub_f32_e32 v6, v91, v1
	v_sub_f32_e32 v7, v117, v1
	v_exp_f32_e32 v6, v6
	v_exp_f32_e32 v7, v7
	v_add_f32_e32 v2, v3, v2
	v_add_f32_e32 v3, v4, v5
	v_sub_f32_e32 v4, v88, v1
	v_sub_f32_e32 v5, v112, v1
	v_add_f32_e32 v2, v3, v2
	v_add_f32_e32 v3, v6, v7
	v_exp_f32_e32 v4, v4
	v_exp_f32_e32 v5, v5
	v_sub_f32_e32 v6, v89, v1
	v_sub_f32_e32 v7, v114, v1
	v_exp_f32_e32 v6, v6
	v_exp_f32_e32 v7, v7
	v_add_f32_e32 v2, v3, v2
	v_add_f32_e32 v3, v4, v5
	v_sub_f32_e32 v4, v100, v1
	v_sub_f32_e32 v5, v108, v1
	v_add_f32_e32 v2, v3, v2
	v_add_f32_e32 v3, v6, v7
	v_exp_f32_e32 v4, v4
	v_exp_f32_e32 v5, v5
	v_sub_f32_e32 v6, v101, v1
	v_sub_f32_e32 v7, v113, v1
	v_exp_f32_e32 v6, v6
	v_exp_f32_e32 v7, v7
	v_add_f32_e32 v2, v3, v2
	v_add_f32_e32 v3, v4, v5
	v_sub_f32_e32 v4, v122, v1
	v_sub_f32_e32 v5, v107, v1
	v_add_f32_e32 v2, v3, v2
	v_add_f32_e32 v3, v6, v7
	v_exp_f32_e32 v4, v4
	v_exp_f32_e32 v5, v5
	v_sub_f32_e32 v6, v125, v1
	v_sub_f32_e32 v7, v109, v1
	v_exp_f32_e32 v6, v6
	v_exp_f32_e32 v7, v7
	v_add_f32_e32 v2, v3, v2
	v_add_f32_e32 v3, v4, v5
	v_sub_f32_e32 v4, v123, v1
	v_sub_f32_e32 v5, v106, v1
	v_add_f32_e32 v2, v3, v2
	v_add_f32_e32 v3, v6, v7
	v_exp_f32_e32 v4, v4
	v_exp_f32_e32 v5, v5
	v_sub_f32_e32 v6, v124, v1
	v_sub_f32_e32 v7, v110, v1
	v_exp_f32_e32 v6, v6
	v_exp_f32_e32 v7, v7
	v_add_f32_e32 v2, v3, v2
	v_add_f32_e32 v3, v4, v5
	v_add_f32_e32 v2, v3, v2
	v_add_f32_e32 v3, v6, v7
	v_add_f32_e32 v2, v3, v2
	v_mov_b32_e32 v3, v2
	s_nop 1
	v_permlane32_swap_b32_e32 v2, v3
	v_add_f32_e32 v2, v2, v3
	v_add_u32_e32 v3, 0x10000, v105
	ds_write_b32 v3, v1
	v_lshl_add_u32 v1, v133, 2, s2
	ds_write_b32 v1, v2 offset:2048
	v_mov_b32_e32 v1, v133
	s_movk_i32 s2, 0x1ff
	v_ashrrev_i32_e32 v2, 1, v1
	v_add_u32_e32 v2, s3, v2
	v_cmp_gt_i32_e32 vcc, s2, v2
	v_lshlrev_b32_e32 v1, 7, v1
	v_and_b32_e32 v4, 0x80, v1
	v_cndmask_b32_e32 v2, 0, v2, vcc
	v_ashrrev_i32_e32 v3, 31, v2
	v_lshl_add_u64 v[2:3], s[60:61], 0, v[2:3]
	v_lshlrev_b64 v[2:3], 8, v[2:3]
	v_lshl_add_u64 v[2:3], s[24:25], 0, v[2:3]
	v_mov_b32_e32 v5, v96
	v_mov_b32_e32 v0, 0
	v_lshl_add_u64 v[32:33], v[2:3], 0, v[4:5]
	v_mov_b32_e32 v4, 0
	v_mov_b32_e32 v5, 0
	v_mov_b32_e32 v6, 0
	v_mov_b32_e32 v7, 0
	v_mov_b32_e32 v9, 0
	v_mov_b32_e32 v10, 0
	v_mov_b32_e32 v11, 0
	s_and_saveexec_b64 s[4:5], vcc
	s_cbranch_execz .LBB0_736
	global_load_dwordx4 v[4:7], v[32:33], off
	global_load_dwordx4 v[8:11], v[32:33], off offset:16

.LBB0_1689:
	v_cndmask_b32_e64 v8, 0, 1, s[24:25]
	v_cmp_ne_u32_e64 s[4:5], 1, v8
	s_andn2_b64 vcc, exec, s[24:25]
	s_cbranch_vccnz .LBB0_1694
	s_lshl_b64 s[2:3], s[20:21], 15
	s_add_u32 s2, s31, s2
	s_addc_u32 s3, s37, s3
	v_lshl_add_u64 v[8:9], v[16:17], 2, s[2:3]
	v_add_co_u32_e32 v8, vcc, 0xffffc000, v8
	s_nop 1
	v_addc_co_u32_e32 v9, vcc, -1, v9, vcc
	global_load_dwordx4 v[8:11], v[8:9], off
	s_and_b64 vcc, exec, s[4:5]
	s_cbranch_vccnz .LBB0_1692
